# P2a segment write-out: first five 64-entry slices read from LDS together and stored behind one wait
# baseline (speedup 1.0000x reference)
.LBB0_1124:
	s_add_i32 s0, s59, s18
	s_add_i32 s0, s0, 1
	s_mul_hi_i32 s1, s0, s58
	s_mul_i32 s0, s0, s58
	s_add_u32 s2, s0, -1
	s_addc_u32 s3, s1, -1
	s_mul_hi_u32 s6, s2, 0xff01fc07
	s_mul_i32 s7, s2, 0xff01fc07
	s_mul_i32 s18, s3, 0xf01fc07f
	s_mul_hi_u32 s2, s2, 0xf01fc07f
	s_mul_hi_u32 s12, s3, 0xf01fc07f
	s_add_u32 s2, s18, s2
	s_addc_u32 s12, s12, 0
	s_add_u32 s2, s7, s2
	s_addc_u32 s2, s6, 0
	s_add_u32 s2, s12, s2
	s_addc_u32 s6, 0, 0
	s_mul_i32 s12, s3, 0xff01fc07
	s_mul_hi_u32 s7, s3, 0xff01fc07
	s_add_u32 s2, s12, s2
	s_addc_u32 s6, s7, s6
	s_ashr_i32 s3, s3, 31
	s_mul_i32 s7, s3, 0xff01fc07
	s_mul_hi_u32 s12, s3, 0xf01fc07f
	s_add_i32 s7, s12, s7
	s_mul_i32 s3, s3, 0xf01fc07f
	s_add_i32 s7, s7, s3
	s_sub_u32 s0, s3, s0
	s_subb_u32 s1, s7, s1
	s_add_u32 s0, s0, s2
	s_addc_u32 s1, s1, s6
	s_add_u32 s0, s0, 1
	s_addc_u32 s1, s1, 0
	s_lshr_b32 s2, s1, 31
	s_lshr_b64 s[0:1], s[0:1], 6
	s_add_i32 s12, s0, s2
	s_and_b64 s[0:1], s[10:11], exec
	s_cselect_b32 s10, 0x80, 0
	v_cmp_gt_i32_e32 vcc, s78, v66
	s_and_saveexec_b64 s[0:1], vcc
	s_mov_b64 s[6:7], 0x100
	s_cbranch_execz .LBB0_1127
	s_add_i32 s3, s10, s29
	s_add_i32 s2, s24, s12
	s_mul_i32 s3, s3, 3
	s_add_i32 s2, s2, s3
	s_ashr_i32 s3, s2, 31
	s_lshl_b64 s[2:3], s[2:3], 17
	v_lshl_add_u64 v[0:1], v[122:123], 0, s[2:3]
	s_mov_b64 s[2:3], 0
	v_mov_b32_e32 v2, v198
	v_mov_b32_e32 v3, v66
	ds_read_b32 v4, v2
	ds_read_b32 v5, v2 offset:256
	ds_read_b32 v6, v2 offset:512
	ds_read_b32 v7, v2 offset:768
	ds_read_b32 v8, v2 offset:1024
	s_waitcnt lgkmcnt(0)
	global_store_dword v[0:1], v4, off
	v_add_u32_e32 v3, 64, v3
	v_cmp_gt_i32_e32 vcc, s78, v3
	s_and_b64 exec, exec, vcc
	global_store_dword v[0:1], v5, off offset:256
	v_add_u32_e32 v3, 64, v3
	v_cmp_gt_i32_e32 vcc, s78, v3
	s_and_b64 exec, exec, vcc
	global_store_dword v[0:1], v6, off offset:512
	v_add_u32_e32 v3, 64, v3
	v_cmp_gt_i32_e32 vcc, s78, v3
	s_and_b64 exec, exec, vcc
	global_store_dword v[0:1], v7, off offset:768
	v_add_u32_e32 v3, 64, v3
	v_cmp_gt_i32_e32 vcc, s78, v3
	s_and_b64 exec, exec, vcc
	global_store_dword v[0:1], v8, off offset:1024
	v_add_u32_e32 v3, 64, v3
	v_cmp_gt_i32_e32 vcc, s78, v3
	s_and_b64 exec, exec, vcc
	s_cbranch_execz .LBB0_1127
	v_add_u32_e32 v2, 0x500, v2
	v_add_co_u32_e32 v0, vcc, 0x500, v0
	s_nop 1
	v_addc_co_u32_e32 v1, vcc, 0, v1, vcc

.LBB0_1185:
	v_cmp_gt_i32_e32 vcc, s61, v66
	s_and_saveexec_b64 s[0:1], vcc
	s_mov_b64 s[18:19], 0x100
	s_cbranch_execz .LBB0_1188
	s_add_i32 s3, s10, s29
	s_add_i32 s2, s24, s12
	s_mul_i32 s3, s3, 3
	s_add_i32 s2, s2, s3
	s_ashr_i32 s3, s2, 31
	s_lshl_b64 s[2:3], s[2:3], 17
	v_lshl_add_u64 v[0:1], v[124:125], 0, s[2:3]
	s_mov_b64 s[2:3], 0
	v_mov_b32_e32 v2, v67
	v_mov_b32_e32 v3, v66
	ds_read_b32 v4, v2
	ds_read_b32 v5, v2 offset:256
	ds_read_b32 v6, v2 offset:512
	ds_read_b32 v7, v2 offset:768
	ds_read_b32 v8, v2 offset:1024
	s_waitcnt lgkmcnt(0)
	global_store_dword v[0:1], v4, off
	v_add_u32_e32 v3, 64, v3
	v_cmp_gt_i32_e32 vcc, s61, v3
	s_and_b64 exec, exec, vcc
	global_store_dword v[0:1], v5, off offset:256
	v_add_u32_e32 v3, 64, v3
	v_cmp_gt_i32_e32 vcc, s61, v3
	s_and_b64 exec, exec, vcc
	global_store_dword v[0:1], v6, off offset:512
	v_add_u32_e32 v3, 64, v3
	v_cmp_gt_i32_e32 vcc, s61, v3
	s_and_b64 exec, exec, vcc
	global_store_dword v[0:1], v7, off offset:768
	v_add_u32_e32 v3, 64, v3
	v_cmp_gt_i32_e32 vcc, s61, v3
	s_and_b64 exec, exec, vcc
	global_store_dword v[0:1], v8, off offset:1024
	v_add_u32_e32 v3, 64, v3
	v_cmp_gt_i32_e32 vcc, s61, v3
	s_and_b64 exec, exec, vcc
	s_cbranch_execz .LBB0_1188
	v_add_u32_e32 v2, 0x500, v2
	v_add_co_u32_e32 v0, vcc, 0x500, v0
	s_nop 1
	v_addc_co_u32_e32 v1, vcc, 0, v1, vcc

.LBB0_1246:
	v_cmp_gt_i32_e32 vcc, s16, v66
	s_and_saveexec_b64 s[0:1], vcc
	s_mov_b64 s[18:19], 0x100
	s_cbranch_execz .LBB0_1249
	s_add_i32 s3, s10, s29
	s_add_i32 s2, s24, s12
	s_mul_i32 s3, s3, 3
	s_add_i32 s2, s2, s3
	s_ashr_i32 s3, s2, 31
	s_lshl_b64 s[2:3], s[2:3], 17
	v_lshl_add_u64 v[0:1], v[126:127], 0, s[2:3]
	s_mov_b64 s[2:3], 0
	v_mov_b32_e32 v2, v217
	v_mov_b32_e32 v3, v66
	ds_read_b32 v4, v2
	ds_read_b32 v5, v2 offset:256
	ds_read_b32 v6, v2 offset:512
	ds_read_b32 v7, v2 offset:768
	ds_read_b32 v8, v2 offset:1024
	s_waitcnt lgkmcnt(0)
	global_store_dword v[0:1], v4, off
	v_add_u32_e32 v3, 64, v3
	v_cmp_gt_i32_e32 vcc, s16, v3
	s_and_b64 exec, exec, vcc
	global_store_dword v[0:1], v5, off offset:256
	v_add_u32_e32 v3, 64, v3
	v_cmp_gt_i32_e32 vcc, s16, v3
	s_and_b64 exec, exec, vcc
	global_store_dword v[0:1], v6, off offset:512
	v_add_u32_e32 v3, 64, v3
	v_cmp_gt_i32_e32 vcc, s16, v3
	s_and_b64 exec, exec, vcc
	global_store_dword v[0:1], v7, off offset:768
	v_add_u32_e32 v3, 64, v3
	v_cmp_gt_i32_e32 vcc, s16, v3
	s_and_b64 exec, exec, vcc
	global_store_dword v[0:1], v8, off offset:1024
	v_add_u32_e32 v3, 64, v3
	v_cmp_gt_i32_e32 vcc, s16, v3
	s_and_b64 exec, exec, vcc
	s_cbranch_execz .LBB0_1249
	v_add_u32_e32 v2, 0x500, v2
	v_add_co_u32_e32 v0, vcc, 0x500, v0
	s_nop 1
	v_addc_co_u32_e32 v1, vcc, 0, v1, vcc

.LBB0_1307:
	v_cmp_gt_i32_e32 vcc, s15, v66
	s_and_saveexec_b64 s[0:1], vcc
	s_mov_b64 s[16:17], 0x100
	s_cbranch_execz .LBB0_1310
	s_add_i32 s3, s10, s29
	s_add_i32 s2, s24, s12
	s_mul_i32 s3, s3, 3
	s_add_i32 s2, s2, s3
	s_ashr_i32 s3, s2, 31
	s_lshl_b64 s[2:3], s[2:3], 17
	v_lshl_add_u64 v[0:1], v[128:129], 0, s[2:3]
	s_mov_b64 s[2:3], 0
	v_mov_b32_e32 v2, v218
	v_mov_b32_e32 v3, v66
	ds_read_b32 v4, v2
	ds_read_b32 v5, v2 offset:256
	ds_read_b32 v6, v2 offset:512
	ds_read_b32 v7, v2 offset:768
	ds_read_b32 v8, v2 offset:1024
	s_waitcnt lgkmcnt(0)
	global_store_dword v[0:1], v4, off
	v_add_u32_e32 v3, 64, v3
	v_cmp_gt_i32_e32 vcc, s15, v3
	s_and_b64 exec, exec, vcc
	global_store_dword v[0:1], v5, off offset:256
	v_add_u32_e32 v3, 64, v3
	v_cmp_gt_i32_e32 vcc, s15, v3
	s_and_b64 exec, exec, vcc
	global_store_dword v[0:1], v6, off offset:512
	v_add_u32_e32 v3, 64, v3
	v_cmp_gt_i32_e32 vcc, s15, v3
	s_and_b64 exec, exec, vcc
	global_store_dword v[0:1], v7, off offset:768
	v_add_u32_e32 v3, 64, v3
	v_cmp_gt_i32_e32 vcc, s15, v3
	s_and_b64 exec, exec, vcc
	global_store_dword v[0:1], v8, off offset:1024
	v_add_u32_e32 v3, 64, v3
	v_cmp_gt_i32_e32 vcc, s15, v3
	s_and_b64 exec, exec, vcc
	s_cbranch_execz .LBB0_1310
	v_add_u32_e32 v2, 0x500, v2
	v_add_co_u32_e32 v0, vcc, 0x500, v0
	s_nop 1
	v_addc_co_u32_e32 v1, vcc, 0, v1, vcc

.LBB0_1368:
	v_cmp_gt_i32_e32 vcc, s8, v66
	s_and_saveexec_b64 s[0:1], vcc
	s_mov_b64 s[16:17], 0x100
	s_cbranch_execz .LBB0_1371
	s_add_i32 s3, s10, s29
	s_add_i32 s2, s24, s12
	s_mul_i32 s3, s3, 3
	s_add_i32 s2, s2, s3
	s_ashr_i32 s3, s2, 31
	s_lshl_b64 s[2:3], s[2:3], 17
	v_lshl_add_u64 v[0:1], v[130:131], 0, s[2:3]
	s_mov_b64 s[2:3], 0
	v_mov_b32_e32 v2, v219
	v_mov_b32_e32 v3, v66
	ds_read_b32 v4, v2
	ds_read_b32 v5, v2 offset:256
	ds_read_b32 v6, v2 offset:512
	ds_read_b32 v7, v2 offset:768
	ds_read_b32 v8, v2 offset:1024
	s_waitcnt lgkmcnt(0)
	global_store_dword v[0:1], v4, off
	v_add_u32_e32 v3, 64, v3
	v_cmp_gt_i32_e32 vcc, s8, v3
	s_and_b64 exec, exec, vcc
	global_store_dword v[0:1], v5, off offset:256
	v_add_u32_e32 v3, 64, v3
	v_cmp_gt_i32_e32 vcc, s8, v3
	s_and_b64 exec, exec, vcc
	global_store_dword v[0:1], v6, off offset:512
	v_add_u32_e32 v3, 64, v3
	v_cmp_gt_i32_e32 vcc, s8, v3
	s_and_b64 exec, exec, vcc
	global_store_dword v[0:1], v7, off offset:768
	v_add_u32_e32 v3, 64, v3
	v_cmp_gt_i32_e32 vcc, s8, v3
	s_and_b64 exec, exec, vcc
	global_store_dword v[0:1], v8, off offset:1024
	v_add_u32_e32 v3, 64, v3
	v_cmp_gt_i32_e32 vcc, s8, v3
	s_and_b64 exec, exec, vcc
	s_cbranch_execz .LBB0_1371
	v_add_u32_e32 v2, 0x500, v2
	v_add_co_u32_e32 v0, vcc, 0x500, v0
	s_nop 1
	v_addc_co_u32_e32 v1, vcc, 0, v1, vcc

.LBB0_1429:
	v_cmp_gt_i32_e32 vcc, s14, v66
	s_and_saveexec_b64 s[0:1], vcc
	s_mov_b64 s[16:17], 0x100
	s_cbranch_execz .LBB0_1432
	s_add_i32 s3, s10, s29
	s_add_i32 s2, s24, s12
	s_mul_i32 s3, s3, 3
	s_add_i32 s2, s2, s3
	s_ashr_i32 s3, s2, 31
	s_lshl_b64 s[2:3], s[2:3], 17
	v_lshl_add_u64 v[0:1], v[132:133], 0, s[2:3]
	s_mov_b64 s[2:3], 0
	v_mov_b32_e32 v2, v220
	v_mov_b32_e32 v3, v66
	ds_read_b32 v4, v2
	ds_read_b32 v5, v2 offset:256
	ds_read_b32 v6, v2 offset:512
	ds_read_b32 v7, v2 offset:768
	ds_read_b32 v8, v2 offset:1024
	s_waitcnt lgkmcnt(0)
	global_store_dword v[0:1], v4, off
	v_add_u32_e32 v3, 64, v3
	v_cmp_gt_i32_e32 vcc, s14, v3
	s_and_b64 exec, exec, vcc
	global_store_dword v[0:1], v5, off offset:256
	v_add_u32_e32 v3, 64, v3
	v_cmp_gt_i32_e32 vcc, s14, v3
	s_and_b64 exec, exec, vcc
	global_store_dword v[0:1], v6, off offset:512
	v_add_u32_e32 v3, 64, v3
	v_cmp_gt_i32_e32 vcc, s14, v3
	s_and_b64 exec, exec, vcc
	global_store_dword v[0:1], v7, off offset:768
	v_add_u32_e32 v3, 64, v3
	v_cmp_gt_i32_e32 vcc, s14, v3
	s_and_b64 exec, exec, vcc
	global_store_dword v[0:1], v8, off offset:1024
	v_add_u32_e32 v3, 64, v3
	v_cmp_gt_i32_e32 vcc, s14, v3
	s_and_b64 exec, exec, vcc
	s_cbranch_execz .LBB0_1432
	v_add_u32_e32 v2, 0x500, v2
	v_add_co_u32_e32 v0, vcc, 0x500, v0
	s_nop 1
	v_addc_co_u32_e32 v1, vcc, 0, v1, vcc

.LBB0_1490:
	v_cmp_gt_i32_e32 vcc, s13, v66
	s_and_saveexec_b64 s[0:1], vcc
	s_mov_b64 s[14:15], 0x100
	s_cbranch_execz .LBB0_1493
	s_add_i32 s3, s10, s29
	s_add_i32 s2, s24, s12
	s_mul_i32 s3, s3, 3
	s_add_i32 s2, s2, s3
	s_ashr_i32 s3, s2, 31
	s_lshl_b64 s[2:3], s[2:3], 17
	v_lshl_add_u64 v[0:1], v[134:135], 0, s[2:3]
	s_mov_b64 s[2:3], 0
	v_mov_b32_e32 v2, v221
	v_mov_b32_e32 v3, v66
	ds_read_b32 v4, v2
	ds_read_b32 v5, v2 offset:256
	ds_read_b32 v6, v2 offset:512
	ds_read_b32 v7, v2 offset:768
	ds_read_b32 v8, v2 offset:1024
	s_waitcnt lgkmcnt(0)
	global_store_dword v[0:1], v4, off
	v_add_u32_e32 v3, 64, v3
	v_cmp_gt_i32_e32 vcc, s13, v3
	s_and_b64 exec, exec, vcc
	global_store_dword v[0:1], v5, off offset:256
	v_add_u32_e32 v3, 64, v3
	v_cmp_gt_i32_e32 vcc, s13, v3
	s_and_b64 exec, exec, vcc
	global_store_dword v[0:1], v6, off offset:512
	v_add_u32_e32 v3, 64, v3
	v_cmp_gt_i32_e32 vcc, s13, v3
	s_and_b64 exec, exec, vcc
	global_store_dword v[0:1], v7, off offset:768
	v_add_u32_e32 v3, 64, v3
	v_cmp_gt_i32_e32 vcc, s13, v3
	s_and_b64 exec, exec, vcc
	global_store_dword v[0:1], v8, off offset:1024
	v_add_u32_e32 v3, 64, v3
	v_cmp_gt_i32_e32 vcc, s13, v3
	s_and_b64 exec, exec, vcc
	s_cbranch_execz .LBB0_1493
	v_add_u32_e32 v2, 0x500, v2
	v_add_co_u32_e32 v0, vcc, 0x500, v0
	s_nop 1
	v_addc_co_u32_e32 v1, vcc, 0, v1, vcc

.LBB0_1551:
	v_cmp_gt_i32_e32 vcc, s5, v66
	s_and_saveexec_b64 s[0:1], vcc
	s_mov_b64 s[8:9], 0x100
	s_cbranch_execz .LBB0_1554
	s_add_i32 s3, s10, s29
	s_add_i32 s2, s24, s12
	s_mul_i32 s3, s3, 3
	s_add_i32 s2, s2, s3
	s_ashr_i32 s3, s2, 31
	s_lshl_b64 s[2:3], s[2:3], 17
	v_lshl_add_u64 v[0:1], v[136:137], 0, s[2:3]
	s_mov_b64 s[2:3], 0
	v_mov_b32_e32 v2, v222
	v_mov_b32_e32 v3, v66
	ds_read_b32 v4, v2
	ds_read_b32 v5, v2 offset:256
	ds_read_b32 v6, v2 offset:512
	ds_read_b32 v7, v2 offset:768
	ds_read_b32 v8, v2 offset:1024
	s_waitcnt lgkmcnt(0)
	global_store_dword v[0:1], v4, off
	v_add_u32_e32 v3, 64, v3
	v_cmp_gt_i32_e32 vcc, s5, v3
	s_and_b64 exec, exec, vcc
	global_store_dword v[0:1], v5, off offset:256
	v_add_u32_e32 v3, 64, v3
	v_cmp_gt_i32_e32 vcc, s5, v3
	s_and_b64 exec, exec, vcc
	global_store_dword v[0:1], v6, off offset:512
	v_add_u32_e32 v3, 64, v3
	v_cmp_gt_i32_e32 vcc, s5, v3
	s_and_b64 exec, exec, vcc
	global_store_dword v[0:1], v7, off offset:768
	v_add_u32_e32 v3, 64, v3
	v_cmp_gt_i32_e32 vcc, s5, v3
	s_and_b64 exec, exec, vcc
	global_store_dword v[0:1], v8, off offset:1024
	v_add_u32_e32 v3, 64, v3
	v_cmp_gt_i32_e32 vcc, s5, v3
	s_and_b64 exec, exec, vcc
	s_cbranch_execz .LBB0_1554
	v_add_u32_e32 v2, 0x500, v2
	v_add_co_u32_e32 v0, vcc, 0x500, v0
	s_nop 1
	v_addc_co_u32_e32 v1, vcc, 0, v1, vcc
